# mini GEMMs and fix-up items: all loads of one operand issued back to back before the next operand's (each 128-byte line's 32-byte pieces requested consecutively), MFMA waits recounted
# baseline (speedup 1.0000x reference)
; __device__ __forceinline__ void up_fixup(const Args& a, LAS unsigned char* lds, int bx, int G, int tid, int wave, int lane) {
;     ...
;     for (int item = bx; item < 176; item += G) {
;         const int mt = item / 88, cp = item % 88, pn = cp >> 2, sub = cp & 3;
;         const bf16_t* ap = hb + (size_t)fix_row(mt * 32 + r) * DM + wave * 128 + 8 * hf;
;         const bf16_t* bg = W + (size_t)(256 * pn + 32 * sub + r) * DM + wave * 128 + 8 * hf; const bf16_t* bv = bg + (size_t)128 * DM;
;         f32x16 ag, av; for (int i = 0; i < 16; ++i) { ag[i] = 0.f; av[i] = 0.f; }
; #pragma unroll
;         for (int k = 0; k < 128; k += 16) { const bf16x8 af = *(const bf16x8*)(ap + k); ag = __builtin_amdgcn_mfma_f32_32x32x16_bf16(af, *(const bf16x8*)(bg + k), ag, 0, 0, 0); av = __builtin_amdgcn_mfma_f32_32x32x16_bf16(af, *(const bf16x8*)(bv + k), av, 0, 0, 0); }
;         __syncthreads();
; #pragma unroll
;         for (int i = 0; i < 16; ++i) { red[((wave * 2 + 0) * 16 + i) * 64 + lane] = ag[i]; red[((wave * 2 + 1) * 16 + i) * 64 + lane] = av[i]; }
;         __syncthreads();
; #pragma unroll
;         for (int h4 = 0; h4 < 4; ++h4) {
;             const int e = tid + h4 * 512, gv = e >> 10, i = (e >> 6) & 15, ln = e & 63;
;             float v = 0.f;
; #pragma unroll
;             for (int w = 0; w < 8; ++w) v += red[((w * 2 + gv) * 16 + i) * 64 + ln];
;             const int ml = (i & 3) + 8 * (i >> 2) + 4 * (ln >> 5);
;             tile[(gv * 32 + ml) * 32 + (ln & 31)] = v * rstd3[fix_row(mt * 32 + ml)];
.LBB0_1175:
	s_mul_hi_i32 s4, s15, 0x2e8ba2e9
	s_lshr_b32 s12, s4, 31
	s_ashr_i32 s4, s4, 4
	s_add_i32 s12, s4, s12
	s_lshl_b32 s26, s12, 5
	v_or_b32_e32 v0, s26, v42
	v_ashrrev_i32_e32 v0, 2, v0
	s_mul_i32 s4, s12, 0xffffffa8
	v_lshl_or_b32 v1, v0, 13, v44
	v_lshl_add_u32 v2, v0, 5, v43
	v_cmp_gt_i32_e32 vcc, 8, v0
	s_add_i32 s4, s15, s4
	s_ashr_i32 s4, s4, 2
	v_cndmask_b32_e32 v0, v2, v1, vcc
	v_ashrrev_i32_e32 v1, 31, v0
	v_lshlrev_b64 v[0:1], 11, v[0:1]
	s_lshl_b32 s13, s4, 8
	s_and_b32 s12, s16, 0x60
	s_or_b32 s13, s13, s12
	v_lshl_add_u64 v[88:89], v[34:35], 0, v[0:1]
	v_or_b32_e32 v2, s13, v42
	v_ashrrev_i32_e32 v3, 31, v2
	v_lshlrev_b64 v[0:1], 11, v[2:3]
	v_lshl_add_u64 v[90:91], v[36:37], 0, v[0:1]
	v_add_co_u32_e32 v92, vcc, s20, v90
	v_or_b32_e32 v32, s26, v47
	s_nop 0
	v_addc_co_u32_e32 v93, vcc, 0, v91, vcc
	v_cmp_gt_i32_e32 vcc, 32, v32
	s_lshl_b32 s4, s4, 7
	s_or_b32 s4, s4, s12
	v_or_b32_e32 v76, s26, v50
	v_lshl_or_b32 v77, v32, 11, v48
	v_lshl_add_u32 v72, v32, 3, v57
	v_lshl_or_b32 v73, v76, 11, v51
	v_lshl_add_u32 v74, v76, 3, v57
	v_cndmask_b32_e32 v72, v72, v77, vcc
	v_cmp_gt_i32_e32 vcc, 32, v76
	s_nop 1
	v_cndmask_b32_e32 v74, v74, v73, vcc
	v_ashrrev_i32_e32 v73, 31, v72
	v_ashrrev_i32_e32 v75, 31, v74
	v_lshl_add_u64 v[68:69], v[72:73], 2, s[10:11]
	v_lshl_add_u64 v[70:71], v[74:75], 2, s[10:11]
	global_load_dwordx4 v[100:103], v[88:89], off
	global_load_dwordx4 v[104:107], v[88:89], off offset:32
	global_load_dwordx4 v[108:111], v[88:89], off offset:64
	global_load_dwordx4 v[112:115], v[88:89], off offset:96
	global_load_dwordx4 v[116:119], v[88:89], off offset:128
	global_load_dwordx4 v[120:123], v[88:89], off offset:160
	global_load_dwordx4 v[124:127], v[88:89], off offset:192
	global_load_dwordx4 v[128:131], v[88:89], off offset:224
	global_load_dwordx4 v[132:135], v[90:91], off
	global_load_dwordx4 v[136:139], v[90:91], off offset:32
	global_load_dwordx4 v[140:143], v[90:91], off offset:64
	global_load_dwordx4 v[144:147], v[90:91], off offset:96
	global_load_dwordx4 v[148:151], v[90:91], off offset:128
	global_load_dwordx4 v[152:155], v[90:91], off offset:160
	global_load_dwordx4 v[156:159], v[90:91], off offset:192
	global_load_dwordx4 v[160:163], v[90:91], off offset:224
	global_load_dwordx4 v[180:183], v[92:93], off
	global_load_dwordx4 v[184:187], v[92:93], off offset:32
	global_load_dwordx4 v[188:191], v[92:93], off offset:64
	global_load_dwordx4 v[192:195], v[92:93], off offset:96
	global_load_dwordx4 v[196:199], v[92:93], off offset:128
	global_load_dwordx4 v[200:203], v[92:93], off offset:160
	global_load_dwordx4 v[204:207], v[92:93], off offset:192
	global_load_dwordx4 v[208:211], v[92:93], off offset:224
	s_waitcnt vmcnt(15)
	v_mfma_f32_32x32x16_bf16 v[0:15], v[100:103], v[132:135], 0
	s_waitcnt vmcnt(7)
	v_mfma_f32_32x32x16_bf16 v[16:31], v[100:103], v[180:183], 0
	s_waitcnt vmcnt(14)
	v_mfma_f32_32x32x16_bf16 v[0:15], v[104:107], v[136:139], v[0:15]
	s_waitcnt vmcnt(6)
	v_mfma_f32_32x32x16_bf16 v[16:31], v[104:107], v[184:187], v[16:31]
	s_waitcnt vmcnt(13)
	v_mfma_f32_32x32x16_bf16 v[0:15], v[108:111], v[140:143], v[0:15]
	s_waitcnt vmcnt(5)
	v_mfma_f32_32x32x16_bf16 v[16:31], v[108:111], v[188:191], v[16:31]
	s_waitcnt vmcnt(12)
	v_mfma_f32_32x32x16_bf16 v[0:15], v[112:115], v[144:147], v[0:15]
	s_waitcnt vmcnt(4)
	v_mfma_f32_32x32x16_bf16 v[16:31], v[112:115], v[192:195], v[16:31]
	s_waitcnt vmcnt(11)
	v_mfma_f32_32x32x16_bf16 v[0:15], v[116:119], v[148:151], v[0:15]
	s_waitcnt vmcnt(3)
	v_mfma_f32_32x32x16_bf16 v[16:31], v[116:119], v[196:199], v[16:31]
	s_waitcnt vmcnt(10)
	v_mfma_f32_32x32x16_bf16 v[0:15], v[120:123], v[152:155], v[0:15]
	s_waitcnt vmcnt(2)
	v_mfma_f32_32x32x16_bf16 v[16:31], v[120:123], v[200:203], v[16:31]
	s_barrier
; __device__ __forceinline__ void up_fixup(const Args& a, LAS unsigned char* lds, int bx, int G, int tid, int wave, int lane) {
;     ...
;         for (int k = 0; k < 128; k += 16) { const bf16x8 af = *(const bf16x8*)(ap + k); ag = __builtin_amdgcn_mfma_f32_32x32x16_bf16(af, *(const bf16x8*)(bg + k), ag, 0, 0, 0); av = __builtin_amdgcn_mfma_f32_32x32x16_bf16(af, *(const bf16x8*)(bv + k), av, 0, 0, 0); }
;         __syncthreads();
; #pragma unroll
;         for (int i = 0; i < 16; ++i) { red[((wave * 2 + 0) * 16 + i) * 64 + lane] = ag[i]; red[((wave * 2 + 1) * 16 + i) * 64 + lane] = av[i]; }
;         __syncthreads();
; #pragma unroll
;         for (int h4 = 0; h4 < 4; ++h4) {
;             const int e = tid + h4 * 512, gv = e >> 10, i = (e >> 6) & 15, ln = e & 63;
;             float v = 0.f;
; #pragma unroll
;             for (int w = 0; w < 8; ++w) v += red[((w * 2 + gv) * 16 + i) * 64 + ln];
;             const int ml = (i & 3) + 8 * (i >> 2) + 4 * (ln >> 5);
;             tile[(gv * 32 + ml) * 32 + (ln & 31)] = v * rstd3[fix_row(mt * 32 + ml)];
;         }
;         __syncthreads();
;         {
;             const int q = tid >> 6, c = tid & 31, part = (tid >> 5) & 1, m0 = 4 * q, b = q;
;             const int j = 128 * pn + 32 * sub + c;
;             if (part == 0) {
;                 const float* cw = a.in[I_FCW]; const float* cb = a.in[I_FCB];
;                 const float ug0 = tile[(m0) * 32 + c], ug1 = tile[(m0 + 1) * 32 + c], uv0 = tile[(32 + m0) * 32 + c], uv1 = tile[(32 + m0 + 1) * 32 + c];
;                 float hg0 = 0.f, hg1 = 0.f, hv0 = 0.f, hv1 = 0.f;
;                 if (mt) { const float* ch = a.in[I_CFFN] + (size_t)(b * 2) * NUP; hg0 = ch[j]; hg1 = ch[NUP + j]; hv0 = ch[DFF + j]; hv1 = ch[NUP + DFF + j]; }
;                 const float wg0 = cw[j], wg1 = cw[NUP + j], wg2 = cw[2 * NUP + j], bgg = cb[j], wv0 = cw[DFF + j], wv1 = cw[NUP + DFF + j], wv2 = cw[2 * NUP + DFF + j], bvv = cb[DFF + j];
;                 const float cg0 = bgg + wg0 * hg0 + wg1 * hg1 + wg2 * ug0, cv0 = bvv + wv0 * hv0 + wv1 * hv1 + wv2 * uv0;
;                 const float cg1 = bgg + wg0 * hg1 + wg1 * ug0 + wg2 * ug1, cv1 = bvv + wv0 * hv1 + wv1 * uv0 + wv2 * uv1;
;                 bf16_t* act = (bf16_t*)(a.ws + WS_ACT);
;                 const int row0 = fix_row(mt * 32 + m0);
	s_waitcnt vmcnt(9)
	v_mfma_f32_32x32x16_bf16 v[0:15], v[124:127], v[156:159], v[0:15]
	s_waitcnt vmcnt(1)
	v_mfma_f32_32x32x16_bf16 v[16:31], v[124:127], v[204:207], v[16:31]
	s_waitcnt vmcnt(8)
	v_mfma_f32_32x32x16_bf16 v[0:15], v[128:131], v[160:163], v[0:15]
	s_waitcnt vmcnt(0)
	v_mfma_f32_32x32x16_bf16 v[16:31], v[128:131], v[208:211], v[16:31]
	s_nop 7
	ds_write2st64_b32 v58, v0, v1 offset1:1
	s_nop 2
	ds_write2st64_b32 v58, v16, v17 offset0:16 offset1:17
	ds_write2st64_b32 v58, v2, v3 offset0:2 offset1:3
	ds_write2st64_b32 v58, v18, v19 offset0:18 offset1:19
	ds_write2st64_b32 v58, v4, v5 offset0:4 offset1:5
	ds_write2st64_b32 v58, v20, v21 offset0:20 offset1:21
	ds_write2st64_b32 v58, v6, v7 offset0:6 offset1:7
	ds_write2st64_b32 v58, v22, v23 offset0:22 offset1:23
	ds_write2st64_b32 v58, v8, v9 offset0:8 offset1:9
	ds_write2st64_b32 v58, v24, v25 offset0:24 offset1:25
	ds_write2st64_b32 v58, v10, v11 offset0:10 offset1:11
	ds_write2st64_b32 v58, v26, v27 offset0:26 offset1:27
	ds_write2st64_b32 v58, v12, v13 offset0:12 offset1:13
	ds_write2st64_b32 v58, v28, v29 offset0:28 offset1:29
	ds_write2st64_b32 v58, v14, v15 offset0:14 offset1:15
	ds_write2st64_b32 v58, v30, v31 offset0:30 offset1:31
	s_waitcnt lgkmcnt(0)
	s_barrier
	global_load_dword v30, v[68:69], off
	global_load_dword v31, v[70:71], off
	v_or_b32_e32 v0, s26, v54
	v_lshl_or_b32 v1, v0, 11, v55
	v_lshl_add_u32 v2, v0, 3, v57
	v_cmp_gt_i32_e32 vcc, 32, v0
	s_nop 1
	v_cndmask_b32_e32 v0, v2, v1, vcc
	v_ashrrev_i32_e32 v1, 31, v0
	v_lshl_add_u64 v[0:1], v[0:1], 2, s[10:11]
	global_load_dword v32, v[0:1], off
	ds_read2st64_b32 v[0:1], v59 offset1:16
	ds_read2st64_b32 v[2:3], v59 offset0:32 offset1:48
	ds_read2st64_b32 v[4:5], v59 offset0:64 offset1:80
	ds_read2st64_b32 v[6:7], v59 offset0:96 offset1:112
	ds_read2st64_b32 v[8:9], v59 offset0:128 offset1:144
	ds_read2st64_b32 v[10:11], v59 offset0:160 offset1:176
	ds_read2st64_b32 v[12:13], v59 offset0:192 offset1:208
	ds_read2st64_b32 v[14:15], v59 offset0:224 offset1:240
	ds_read2st64_b32 v[16:17], v60 offset1:32
	ds_read2st64_b32 v[18:19], v60 offset0:64 offset1:96
	ds_read2st64_b32 v[20:21], v60 offset0:128 offset1:160
	ds_read2st64_b32 v[22:23], v60 offset0:192 offset1:224
	ds_read2st64_b32 v[24:25], v61 offset1:32
	ds_read2st64_b32 v[26:27], v61 offset0:64 offset1:96
	ds_read2st64_b32 v[28:29], v61 offset0:128 offset1:160
	s_waitcnt lgkmcnt(14)
	v_add_f32_e32 v0, 0, v0
	s_waitcnt lgkmcnt(6)
	v_add_f32_e32 v16, 0, v16
	v_add_f32_e32 v1, 0, v1
	v_add_f32_e32 v0, v0, v2
	v_add_f32_e32 v2, v16, v17
	v_add_f32_e32 v1, v1, v3
	v_add_f32_e32 v0, v0, v4
	s_waitcnt lgkmcnt(5)
	v_add_f32_e32 v2, v2, v18
	v_add_f32_e32 v1, v1, v5
	v_add_f32_e32 v0, v0, v6
	v_add_f32_e32 v2, v2, v19
	v_add_f32_e32 v1, v1, v7
	v_add_f32_e32 v0, v0, v8
	s_waitcnt lgkmcnt(4)
	v_add_f32_e32 v2, v2, v20
	v_add_f32_e32 v1, v1, v9
	v_add_f32_e32 v0, v0, v10
	v_add_f32_e32 v2, v2, v21
	v_add_f32_e32 v1, v1, v11
	v_add_f32_e32 v0, v0, v12
	s_waitcnt lgkmcnt(3)
	v_add_f32_e32 v2, v2, v22
	v_add_f32_e32 v1, v1, v13
	v_add_f32_e32 v0, v0, v14
	v_add_f32_e32 v2, v2, v23
	v_add_f32_e32 v1, v1, v15
	s_waitcnt lgkmcnt(2)
	v_add_f32_e32 v24, 0, v24
	v_add_f32_e32 v3, v24, v25
	s_waitcnt vmcnt(2)
	v_mul_f32_e32 v0, v0, v30
	s_waitcnt vmcnt(1)
	v_mul_f32_e32 v2, v2, v31
	v_mul_f32_e32 v1, v1, v30
	ds_write_b32 v49, v0
	ds_write_b32 v52, v2
	ds_write_b32 v53, v1
	ds_read2st64_b32 v[0:1], v61 offset0:192 offset1:224
	s_waitcnt lgkmcnt(5)
	v_add_f32_e32 v2, v3, v26
	v_add_f32_e32 v2, v2, v27
	s_waitcnt lgkmcnt(4)
	v_add_f32_e32 v2, v2, v28
	v_add_f32_e32 v2, v2, v29
	s_waitcnt lgkmcnt(0)
	v_add_f32_e32 v0, v2, v0
	v_add_f32_e32 v0, v0, v1
	s_waitcnt vmcnt(0)
	v_mul_f32_e32 v0, v0, v32
	v_or_b32_e32 v2, s4, v42
	ds_write_b32 v56, v0
	s_waitcnt lgkmcnt(0)
	s_barrier
	s_and_saveexec_b64 s[12:13], s[0:1]
	s_xor_b64 s[12:13], exec, s[12:13]
	s_cbranch_execz .LBB0_1177
	s_add_i32 s4, s15, 0x57
	s_cmpk_lt_u32 s4, 0xaf
	ds_read2_b32 v[0:1], v46 offset0:64 offset1:96
	s_cselect_b32 s4, s21, 0x105c8000
	v_lshl_add_u64 v[4:5], v[38:39], 0, s[4:5]
	v_ashrrev_i32_e32 v3, 31, v2
	v_lshl_add_u64 v[2:3], v[2:3], 2, v[4:5]
	v_add_co_u32_e32 v4, vcc, 0x5000, v2
	s_waitcnt lgkmcnt(0)
	global_store_dword v[2:3], v0, off
	v_addc_co_u32_e32 v5, vcc, 0, v3, vcc
	v_add_u32_e32 v0, 0x1000, v46
	global_store_dword v[4:5], v1, off offset:2048
	ds_read2_b32 v[0:1], v0 offset0:64 offset1:96
	v_add_co_u32_e32 v4, vcc, 0x2000, v2
	s_nop 1
	v_addc_co_u32_e32 v5, vcc, 0, v3, vcc
	v_add_co_u32_e32 v2, vcc, 0x8000, v2
	s_waitcnt lgkmcnt(0)
	global_store_dword v[4:5], v0, off offset:3072
	v_addc_co_u32_e32 v3, vcc, 0, v3, vcc
	global_store_dword v[2:3], v1, off offset:1024
